# FFN-in mainloop: LDS-DMA loads use SGPR base + 32-bit VGPR offset (16 per-DMA 64-bit VALU address adds removed)
# speedup vs baseline: 1.0188x; 1.0188x over previous
; #define PG8_STAGE(bufoff, gbase, voff) do { _Pragma("unroll") for (int _i = 0; _i < 2; ++_i) \
;         __builtin_amdgcn_global_load_lds((const unsigned*)((const char*)(gbase) + (voff)[_i]), (LAS unsigned*)(lds + (bufoff) + ldsw + _i * 8192), 16, 0, 0); } while (0)
; #define PG8_LDA(dst, b, h) do { _Pragma("unroll") for (int m = 0; m < 4; ++m) _Pragma("unroll") for (int k = 0; k < 2; ++k) dst[m][k] = *(const LAS bf16x8*)(lds + PG8_SA(b, h) + aoff + m * 2048 + k * 1024); } while (0)
; #define PG8_LDB(dst, b, h) do { _Pragma("unroll") for (int n = 0; n < 2; ++n) _Pragma("unroll") for (int k = 0; k < 2; ++k) dst[n][k] = *(const LAS bf16x8*)(lds + PG8_SB(b, h) + boff + n * 2048 + k * 1024); } while (0)
; #define PG8_MMA(ai, bj, At, Bt) do { __builtin_amdgcn_s_setprio(1); _Pragma("unroll") for (int m = 0; m < 4; ++m) _Pragma("unroll") for (int n = 0; n < 2; ++n) _Pragma("unroll") for (int k = 0; k < 2; ++k) \
;         acc[ai][bj][m][n] = __builtin_amdgcn_mfma_f32_16x16x32_bf16(Bt[n][k], At[m][k], acc[ai][bj][m][n], 0, 0, 0); __builtin_amdgcn_s_setprio(0); } while (0)
; #define PG8_WAIT_V(n) asm volatile("s_waitcnt vmcnt(" #n ")" ::: "memory")
; #define PG8_WAIT_L(n) asm volatile("s_waitcnt lgkmcnt(" #n ")" ::: "memory")
; #define PG8_BAR __builtin_amdgcn_s_barrier()
; #define PG8_SCHED __builtin_amdgcn_sched_barrier(0)
; template <class Epi, class Sched>
; __device__ __forceinline__ void gemm_phase(LAS unsigned char* lds, const Gemm g, Sched S, const Epi& E) {
;     ...
;             const bool last = (t == nt - 2);
;             const char* a1 = cA + (size_t)(t + 1) * kstep;
;             const char* a2 = last ? nA : cA + (size_t)(t + 2) * kstep; const char* b2 = last ? nB : cB + (size_t)(t + 2) * kstep;
;             const char* a3 = a2 + kstep; const char* b3 = b2 + kstep;
;             PG8_LDB(B0, 0, 0); PG8_LDB(B1, 0, 1); PG8_SCHED; PG8_LDA(At, 0, 0); PG8_STAGE(PG8_SA(1, 1), a1 + hstepA, voffA);
;             PG8_WAIT_V(8); PG8_WAIT_L(0); PG8_BAR; PG8_MMA(0, 0, At, B0); PG8_MMA(0, 1, At, B1); PG8_BAR; PG8_SCHED;
;             PG8_LDA(At, 0, 1); PG8_STAGE(PG8_SB(0, 0), b2, voffB); PG8_STAGE(PG8_SB(0, 1), b2 + hstepB, voffB); PG8_STAGE(PG8_SA(0, 0), a2, voffA);
;             PG8_WAIT_V(8); PG8_WAIT_L(0); PG8_BAR; PG8_MMA(1, 0, At, B0); PG8_MMA(1, 1, At, B1); PG8_BAR; PG8_SCHED;
.LBB0_770:
	s_add_u32 s3, s10, 0xfffc0080
	s_addc_u32 s42, s11, -1
	s_add_i32 s71, 0, 0x10000
	s_cmp_eq_u32 s70, 12
	s_cselect_b32 s45, s60, s42
	s_cselect_b32 s44, s61, s3
	s_cselect_b32 s43, s62, s65
	s_cselect_b32 s42, s63, s64
	s_add_i32 s3, 0, 0x14000
	v_add_u32_e32 v142, s71, v183
	v_add_u32_e32 v158, s3, v183
	ds_read_b128 v[130:133], v142
	ds_read_b128 v[134:137], v142 offset:1024
	ds_read_b128 v[138:141], v142 offset:2048
	ds_read_b128 v[142:145], v142 offset:3072
	ds_read_b128 v[146:149], v158
	ds_read_b128 v[150:153], v158 offset:1024
	ds_read_b128 v[154:157], v158 offset:2048
	ds_read_b128 v[158:161], v158 offset:3072
	s_add_i32 m0, s9, 0xc000
	ds_read_b128 v[174:177], v194
	ds_read_b128 v[196:199], v194 offset:1024
	ds_read_b128 v[200:203], v194 offset:2048
	ds_read_b128 v[204:207], v194 offset:3072
	ds_read_b128 v[208:211], v194 offset:4096
	ds_read_b128 v[212:215], v194 offset:5120
	ds_read_b128 v[216:219], v194 offset:6144
	ds_read_b128 v[220:223], v194 offset:7168
	global_load_lds_dwordx4 v172, s[10:11]
	s_add_i32 m0, s9, 0xe000
	s_nop 0
	global_load_lds_dwordx4 v170, s[10:11]
	s_waitcnt vmcnt(8)
	s_waitcnt lgkmcnt(0)
	s_barrier
	s_setprio 1
	s_waitcnt lgkmcnt(0)
	v_mfma_f32_16x16x32_bf16 v[126:129], v[130:133], v[174:177], v[126:129]
	v_mfma_f32_16x16x32_bf16 v[118:121], v[138:141], v[174:177], v[118:121]
	v_mfma_f32_16x16x32_bf16 v[110:113], v[130:133], v[200:203], v[110:113]
	v_mfma_f32_16x16x32_bf16 v[102:105], v[138:141], v[200:203], v[102:105]
	v_mfma_f32_16x16x32_bf16 v[94:97], v[130:133], v[208:211], v[94:97]
	v_mfma_f32_16x16x32_bf16 v[86:89], v[138:141], v[208:211], v[86:89]
	v_mfma_f32_16x16x32_bf16 v[78:81], v[130:133], v[216:219], v[78:81]
	v_mfma_f32_16x16x32_bf16 v[70:73], v[138:141], v[216:219], v[70:73]
	v_mfma_f32_16x16x32_bf16 v[126:129], v[134:137], v[196:199], v[126:129]
	v_mfma_f32_16x16x32_bf16 v[118:121], v[142:145], v[196:199], v[118:121]
	v_mfma_f32_16x16x32_bf16 v[110:113], v[134:137], v[204:207], v[110:113]
	v_mfma_f32_16x16x32_bf16 v[102:105], v[142:145], v[204:207], v[102:105]
	v_mfma_f32_16x16x32_bf16 v[94:97], v[134:137], v[212:215], v[94:97]
	v_mfma_f32_16x16x32_bf16 v[86:89], v[142:145], v[212:215], v[86:89]
	v_mfma_f32_16x16x32_bf16 v[78:81], v[134:137], v[220:223], v[78:81]
	v_mfma_f32_16x16x32_bf16 v[70:73], v[142:145], v[220:223], v[70:73]
	s_setprio 0
	s_setprio 1
	v_mfma_f32_16x16x32_bf16 v[122:125], v[146:149], v[174:177], v[122:125]
	v_mfma_f32_16x16x32_bf16 v[114:117], v[154:157], v[174:177], v[114:117]
	v_mfma_f32_16x16x32_bf16 v[106:109], v[146:149], v[200:203], v[106:109]
	v_mfma_f32_16x16x32_bf16 v[98:101], v[154:157], v[200:203], v[98:101]
	v_mfma_f32_16x16x32_bf16 v[90:93], v[146:149], v[208:211], v[90:93]
	v_mfma_f32_16x16x32_bf16 v[82:85], v[154:157], v[208:211], v[82:85]
	v_mfma_f32_16x16x32_bf16 v[74:77], v[146:149], v[216:219], v[74:77]
	v_mfma_f32_16x16x32_bf16 v[66:69], v[154:157], v[216:219], v[66:69]
	v_mfma_f32_16x16x32_bf16 v[122:125], v[150:153], v[196:199], v[122:125]
	v_mfma_f32_16x16x32_bf16 v[114:117], v[158:161], v[196:199], v[114:117]
	v_mfma_f32_16x16x32_bf16 v[106:109], v[150:153], v[204:207], v[106:109]
	v_mfma_f32_16x16x32_bf16 v[98:101], v[158:161], v[204:207], v[98:101]
	v_mfma_f32_16x16x32_bf16 v[90:93], v[150:153], v[212:215], v[90:93]
	v_mfma_f32_16x16x32_bf16 v[82:85], v[158:161], v[212:215], v[82:85]
	v_mfma_f32_16x16x32_bf16 v[74:77], v[150:153], v[220:223], v[74:77]
	v_mfma_f32_16x16x32_bf16 v[66:69], v[158:161], v[220:223], v[66:69]
	s_setprio 0
	s_barrier
	s_add_i32 s71, s71, s7
	s_mov_b32 m0, s71
	ds_read_b128 v[174:177], v194 offset:16384
	ds_read_b128 v[196:199], v194 offset:17408
	ds_read_b128 v[200:203], v194 offset:18432
	ds_read_b128 v[204:207], v194 offset:19456
	ds_read_b128 v[208:211], v194 offset:20480
	ds_read_b128 v[212:215], v194 offset:21504
	ds_read_b128 v[216:219], v194 offset:22528
	ds_read_b128 v[220:223], v194 offset:23552
	global_load_lds_dwordx4 v0, s[42:43]
	s_add_i32 m0, s71, 0x2000
	s_add_u32 s96, s42, 0x40000
	s_addc_u32 s97, s43, 0
	s_add_i32 s3, s3, s7
	global_load_lds_dwordx4 v164, s[42:43]
	s_mov_b32 m0, s3
	s_nop 0
	global_load_lds_dwordx4 v0, s[96:97]
	s_add_i32 m0, s3, 0x2000
	s_nop 0
	global_load_lds_dwordx4 v164, s[96:97]
	s_mov_b32 m0, s9
	s_nop 0
	global_load_lds_dwordx4 v168, s[44:45]
	s_mov_b32 m0, s56
	s_nop 0
	global_load_lds_dwordx4 v166, s[44:45]
	s_waitcnt vmcnt(8)
	s_waitcnt lgkmcnt(0)
	s_barrier
	s_setprio 1
	s_waitcnt lgkmcnt(0)
	v_mfma_f32_16x16x32_bf16 v[62:65], v[130:133], v[174:177], v[62:65]
	v_mfma_f32_16x16x32_bf16 v[54:57], v[138:141], v[174:177], v[54:57]
	v_mfma_f32_16x16x32_bf16 v[46:49], v[130:133], v[200:203], v[46:49]
	v_mfma_f32_16x16x32_bf16 v[38:41], v[138:141], v[200:203], v[38:41]
	v_mfma_f32_16x16x32_bf16 v[30:33], v[130:133], v[208:211], v[30:33]
	v_mfma_f32_16x16x32_bf16 v[22:25], v[138:141], v[208:211], v[22:25]
	v_mfma_f32_16x16x32_bf16 v[14:17], v[130:133], v[216:219], v[14:17]
	v_mfma_f32_16x16x32_bf16 v[6:9], v[138:141], v[216:219], v[6:9]
	v_mfma_f32_16x16x32_bf16 v[62:65], v[134:137], v[196:199], v[62:65]
	v_mfma_f32_16x16x32_bf16 v[54:57], v[142:145], v[196:199], v[54:57]
	v_mfma_f32_16x16x32_bf16 v[46:49], v[134:137], v[204:207], v[46:49]
	v_mfma_f32_16x16x32_bf16 v[38:41], v[142:145], v[204:207], v[38:41]
	v_mfma_f32_16x16x32_bf16 v[30:33], v[134:137], v[212:215], v[30:33]
	v_mfma_f32_16x16x32_bf16 v[22:25], v[142:145], v[212:215], v[22:25]
	v_mfma_f32_16x16x32_bf16 v[14:17], v[134:137], v[220:223], v[14:17]
	v_mfma_f32_16x16x32_bf16 v[6:9], v[142:145], v[220:223], v[6:9]
	s_setprio 0
	s_setprio 1
	v_mfma_f32_16x16x32_bf16 v[58:61], v[146:149], v[174:177], v[58:61]
	v_mfma_f32_16x16x32_bf16 v[50:53], v[154:157], v[174:177], v[50:53]
	v_mfma_f32_16x16x32_bf16 v[42:45], v[146:149], v[200:203], v[42:45]
	v_mfma_f32_16x16x32_bf16 v[34:37], v[154:157], v[200:203], v[34:37]
	v_mfma_f32_16x16x32_bf16 v[26:29], v[146:149], v[208:211], v[26:29]
	v_mfma_f32_16x16x32_bf16 v[18:21], v[154:157], v[208:211], v[18:21]
	v_mfma_f32_16x16x32_bf16 v[10:13], v[146:149], v[216:219], v[10:13]
	v_mfma_f32_16x16x32_bf16 v[2:5], v[154:157], v[216:219], v[2:5]
	v_mfma_f32_16x16x32_bf16 v[58:61], v[150:153], v[196:199], v[58:61]
	v_mfma_f32_16x16x32_bf16 v[50:53], v[158:161], v[196:199], v[50:53]
	v_mfma_f32_16x16x32_bf16 v[42:45], v[150:153], v[204:207], v[42:45]
	v_mfma_f32_16x16x32_bf16 v[34:37], v[158:161], v[204:207], v[34:37]
	v_mfma_f32_16x16x32_bf16 v[26:29], v[150:153], v[212:215], v[26:29]
	v_mfma_f32_16x16x32_bf16 v[18:21], v[158:161], v[212:215], v[18:21]
	v_mfma_f32_16x16x32_bf16 v[10:13], v[150:153], v[220:223], v[10:13]
	v_mfma_f32_16x16x32_bf16 v[2:5], v[158:161], v[220:223], v[2:5]
	s_setprio 0
	s_barrier
; #define PG8_STAGE(bufoff, gbase, voff) do { _Pragma("unroll") for (int _i = 0; _i < 2; ++_i) \
;         __builtin_amdgcn_global_load_lds((const unsigned*)((const char*)(gbase) + (voff)[_i]), (LAS unsigned*)(lds + (bufoff) + ldsw + _i * 8192), 16, 0, 0); } while (0)
; #define PG8_LDA(dst, b, h) do { _Pragma("unroll") for (int m = 0; m < 4; ++m) _Pragma("unroll") for (int k = 0; k < 2; ++k) dst[m][k] = *(const LAS bf16x8*)(lds + PG8_SA(b, h) + aoff + m * 2048 + k * 1024); } while (0)
; #define PG8_LDB(dst, b, h) do { _Pragma("unroll") for (int n = 0; n < 2; ++n) _Pragma("unroll") for (int k = 0; k < 2; ++k) dst[n][k] = *(const LAS bf16x8*)(lds + PG8_SB(b, h) + boff + n * 2048 + k * 1024); } while (0)
; #define PG8_MMA(ai, bj, At, Bt) do { __builtin_amdgcn_s_setprio(1); _Pragma("unroll") for (int m = 0; m < 4; ++m) _Pragma("unroll") for (int n = 0; n < 2; ++n) _Pragma("unroll") for (int k = 0; k < 2; ++k) \
;         acc[ai][bj][m][n] = __builtin_amdgcn_mfma_f32_16x16x32_bf16(Bt[n][k], At[m][k], acc[ai][bj][m][n], 0, 0, 0); __builtin_amdgcn_s_setprio(0); } while (0)
; #define PG8_WAIT_V(n) asm volatile("s_waitcnt vmcnt(" #n ")" ::: "memory")
; #define PG8_WAIT_L(n) asm volatile("s_waitcnt lgkmcnt(" #n ")" ::: "memory")
; #define PG8_BAR __builtin_amdgcn_s_barrier()
; #define PG8_SCHED __builtin_amdgcn_sched_barrier(0)
; template <class Epi, class Sched>
; __device__ __forceinline__ void gemm_phase(LAS unsigned char* lds, const Gemm g, Sched S, const Epi& E) {
;     ...
;             PG8_LDB(B0, 1, 0); PG8_LDB(B1, 1, 1); PG8_SCHED; PG8_LDA(At, 1, 0); PG8_STAGE(PG8_SA(0, 1), a2 + hstepA, voffA);
;             PG8_WAIT_V(8); PG8_WAIT_L(0); PG8_BAR; PG8_MMA(0, 0, At, B0); PG8_MMA(0, 1, At, B1); PG8_BAR; PG8_SCHED;
;             PG8_LDA(At, 1, 1); PG8_STAGE(PG8_SB(1, 0), b3, voffB); PG8_STAGE(PG8_SB(1, 1), b3 + hstepB, voffB); PG8_STAGE(PG8_SA(1, 0), a3, voffA);
;             PG8_WAIT_V(8); PG8_WAIT_L(0); PG8_BAR; PG8_MMA(1, 0, At, B0); PG8_MMA(1, 1, At, B1); PG8_BAR; PG8_SCHED;
;         }
	s_add_i32 s3, 0, 0x18000
	s_add_i32 s71, 0, 0x1c000
	v_add_u32_e32 v142, s3, v183
	v_add_u32_e32 v158, s71, v183
	ds_read_b128 v[130:133], v142
	ds_read_b128 v[134:137], v142 offset:1024
	ds_read_b128 v[138:141], v142 offset:2048
	ds_read_b128 v[142:145], v142 offset:3072
	ds_read_b128 v[146:149], v158
	ds_read_b128 v[150:153], v158 offset:1024
	ds_read_b128 v[154:157], v158 offset:2048
	ds_read_b128 v[158:161], v158 offset:3072
	s_add_u32 s44, s44, 0x40000
	s_addc_u32 s45, s45, 0
	s_mov_b32 m0, s67
	ds_read_b128 v[174:177], v194 offset:32768
	ds_read_b128 v[196:199], v194 offset:33792
	ds_read_b128 v[200:203], v194 offset:34816
	ds_read_b128 v[204:207], v194 offset:35840
	ds_read_b128 v[208:211], v194 offset:36864
	ds_read_b128 v[212:215], v194 offset:37888
	ds_read_b128 v[216:219], v194 offset:38912
	ds_read_b128 v[220:223], v194 offset:39936
	global_load_lds_dwordx4 v168, s[44:45]
	s_mov_b32 m0, s72
	s_nop 0
	global_load_lds_dwordx4 v166, s[44:45]
	s_waitcnt vmcnt(8)
	s_waitcnt lgkmcnt(0)
	s_barrier
	s_setprio 1
	s_waitcnt lgkmcnt(0)
	v_mfma_f32_16x16x32_bf16 v[126:129], v[130:133], v[174:177], v[126:129]
	v_mfma_f32_16x16x32_bf16 v[118:121], v[138:141], v[174:177], v[118:121]
	v_mfma_f32_16x16x32_bf16 v[110:113], v[130:133], v[200:203], v[110:113]
	v_mfma_f32_16x16x32_bf16 v[102:105], v[138:141], v[200:203], v[102:105]
	v_mfma_f32_16x16x32_bf16 v[94:97], v[130:133], v[208:211], v[94:97]
	v_mfma_f32_16x16x32_bf16 v[86:89], v[138:141], v[208:211], v[86:89]
	v_mfma_f32_16x16x32_bf16 v[78:81], v[130:133], v[216:219], v[78:81]
	v_mfma_f32_16x16x32_bf16 v[70:73], v[138:141], v[216:219], v[70:73]
	v_mfma_f32_16x16x32_bf16 v[126:129], v[134:137], v[196:199], v[126:129]
	v_mfma_f32_16x16x32_bf16 v[118:121], v[142:145], v[196:199], v[118:121]
	v_mfma_f32_16x16x32_bf16 v[110:113], v[134:137], v[204:207], v[110:113]
	v_mfma_f32_16x16x32_bf16 v[102:105], v[142:145], v[204:207], v[102:105]
	v_mfma_f32_16x16x32_bf16 v[94:97], v[134:137], v[212:215], v[94:97]
	v_mfma_f32_16x16x32_bf16 v[86:89], v[142:145], v[212:215], v[86:89]
	v_mfma_f32_16x16x32_bf16 v[78:81], v[134:137], v[220:223], v[78:81]
	v_mfma_f32_16x16x32_bf16 v[70:73], v[142:145], v[220:223], v[70:73]
	s_setprio 0
	s_setprio 1
	v_mfma_f32_16x16x32_bf16 v[122:125], v[146:149], v[174:177], v[122:125]
	v_mfma_f32_16x16x32_bf16 v[114:117], v[154:157], v[174:177], v[114:117]
	v_mfma_f32_16x16x32_bf16 v[106:109], v[146:149], v[200:203], v[106:109]
	v_mfma_f32_16x16x32_bf16 v[98:101], v[154:157], v[200:203], v[98:101]
	v_mfma_f32_16x16x32_bf16 v[90:93], v[146:149], v[208:211], v[90:93]
	v_mfma_f32_16x16x32_bf16 v[82:85], v[154:157], v[208:211], v[82:85]
	v_mfma_f32_16x16x32_bf16 v[74:77], v[146:149], v[216:219], v[74:77]
	v_mfma_f32_16x16x32_bf16 v[66:69], v[154:157], v[216:219], v[66:69]
	v_mfma_f32_16x16x32_bf16 v[122:125], v[150:153], v[196:199], v[122:125]
	v_mfma_f32_16x16x32_bf16 v[114:117], v[158:161], v[196:199], v[114:117]
	v_mfma_f32_16x16x32_bf16 v[106:109], v[150:153], v[204:207], v[106:109]
	v_mfma_f32_16x16x32_bf16 v[98:101], v[158:161], v[204:207], v[98:101]
	v_mfma_f32_16x16x32_bf16 v[90:93], v[150:153], v[212:215], v[90:93]
	v_mfma_f32_16x16x32_bf16 v[82:85], v[158:161], v[212:215], v[82:85]
	v_mfma_f32_16x16x32_bf16 v[74:77], v[150:153], v[220:223], v[74:77]
	v_mfma_f32_16x16x32_bf16 v[66:69], v[158:161], v[220:223], v[66:69]
	s_setprio 0
	s_barrier
	s_add_i32 s3, s3, s7
	s_add_u32 s100, s42, 0x80
	s_addc_u32 s101, s43, 0
	s_mov_b32 m0, s3
	ds_read_b128 v[174:177], v194 offset:49152
	ds_read_b128 v[196:199], v194 offset:50176
	ds_read_b128 v[200:203], v194 offset:51200
	ds_read_b128 v[204:207], v194 offset:52224
	ds_read_b128 v[208:211], v194 offset:53248
	ds_read_b128 v[212:215], v194 offset:54272
	ds_read_b128 v[216:219], v194 offset:55296
	ds_read_b128 v[220:223], v194 offset:56320
	global_load_lds_dwordx4 v0, s[100:101]
	s_add_i32 m0, s3, 0x2000
	s_add_u32 s42, s42, 0x40080
	s_addc_u32 s43, s43, 0
	s_add_u32 s96, s44, 0xfffc0080
	s_addc_u32 s97, s45, -1
	s_add_i32 s3, s71, s7
	global_load_lds_dwordx4 v164, s[100:101]
	s_mov_b32 m0, s3
	s_nop 0
	global_load_lds_dwordx4 v0, s[42:43]
	s_add_i32 m0, s3, 0x2000
	s_nop 0
	global_load_lds_dwordx4 v164, s[42:43]
	s_mov_b32 m0, s73
	s_nop 0
	global_load_lds_dwordx4 v168, s[96:97]
	s_mov_b32 m0, s76
	s_nop 0
	global_load_lds_dwordx4 v166, s[96:97]
	s_waitcnt vmcnt(8)
	s_waitcnt lgkmcnt(0)
	s_barrier
	s_setprio 1
	s_waitcnt lgkmcnt(0)
	v_mfma_f32_16x16x32_bf16 v[62:65], v[130:133], v[174:177], v[62:65]
	v_mfma_f32_16x16x32_bf16 v[54:57], v[138:141], v[174:177], v[54:57]
	v_mfma_f32_16x16x32_bf16 v[46:49], v[130:133], v[200:203], v[46:49]
	v_mfma_f32_16x16x32_bf16 v[38:41], v[138:141], v[200:203], v[38:41]
	v_mfma_f32_16x16x32_bf16 v[30:33], v[130:133], v[208:211], v[30:33]
	v_mfma_f32_16x16x32_bf16 v[22:25], v[138:141], v[208:211], v[22:25]
	v_mfma_f32_16x16x32_bf16 v[14:17], v[130:133], v[216:219], v[14:17]
	v_mfma_f32_16x16x32_bf16 v[6:9], v[138:141], v[216:219], v[6:9]
	v_mfma_f32_16x16x32_bf16 v[62:65], v[134:137], v[196:199], v[62:65]
	v_mfma_f32_16x16x32_bf16 v[54:57], v[142:145], v[196:199], v[54:57]
	v_mfma_f32_16x16x32_bf16 v[46:49], v[134:137], v[204:207], v[46:49]
	v_mfma_f32_16x16x32_bf16 v[38:41], v[142:145], v[204:207], v[38:41]
	v_mfma_f32_16x16x32_bf16 v[30:33], v[134:137], v[212:215], v[30:33]
	v_mfma_f32_16x16x32_bf16 v[22:25], v[142:145], v[212:215], v[22:25]
	v_mfma_f32_16x16x32_bf16 v[14:17], v[134:137], v[220:223], v[14:17]
	v_mfma_f32_16x16x32_bf16 v[6:9], v[142:145], v[220:223], v[6:9]
	s_setprio 0
	s_setprio 1
	v_mfma_f32_16x16x32_bf16 v[58:61], v[146:149], v[174:177], v[58:61]
	v_mfma_f32_16x16x32_bf16 v[50:53], v[154:157], v[174:177], v[50:53]
	v_mfma_f32_16x16x32_bf16 v[42:45], v[146:149], v[200:203], v[42:45]
	v_mfma_f32_16x16x32_bf16 v[34:37], v[154:157], v[200:203], v[34:37]
	v_mfma_f32_16x16x32_bf16 v[26:29], v[146:149], v[208:211], v[26:29]
	v_mfma_f32_16x16x32_bf16 v[18:21], v[154:157], v[208:211], v[18:21]
	v_mfma_f32_16x16x32_bf16 v[10:13], v[146:149], v[216:219], v[10:13]
	v_mfma_f32_16x16x32_bf16 v[2:5], v[154:157], v[216:219], v[2:5]
	v_mfma_f32_16x16x32_bf16 v[58:61], v[150:153], v[196:199], v[58:61]
	v_mfma_f32_16x16x32_bf16 v[50:53], v[158:161], v[196:199], v[50:53]
	v_mfma_f32_16x16x32_bf16 v[42:45], v[150:153], v[204:207], v[42:45]
	v_mfma_f32_16x16x32_bf16 v[34:37], v[158:161], v[204:207], v[34:37]
	v_mfma_f32_16x16x32_bf16 v[26:29], v[150:153], v[212:215], v[26:29]
	v_mfma_f32_16x16x32_bf16 v[18:21], v[158:161], v[212:215], v[18:21]
	v_mfma_f32_16x16x32_bf16 v[10:13], v[150:153], v[220:223], v[10:13]
	v_mfma_f32_16x16x32_bf16 v[2:5], v[158:161], v[220:223], v[2:5]
	s_setprio 0
	s_barrier
	s_add_i32 s70, s70, 2
	s_add_u32 s64, s64, 0x100
	s_addc_u32 s65, s65, 0
	s_add_u32 s10, s10, 0x100
	s_addc_u32 s11, s11, 0
	s_cmp_gt_u32 s70, 13
	s_cbranch_scc0 .LBB0_770
	s_and_b64 vcc, exec, s[30:31]
	s_cbranch_vccz .LBB0_773
	s_barrier

; __global__ void __launch_bounds__(512, 2) fwd_kernel(Args args) {
;     extern __shared__ __attribute__((aligned(16))) unsigned char lds_raw[];
	.amdhsa_kernel _Z10fwd_kernel4Args
		.amdhsa_group_segment_fixed_size 0
		.amdhsa_private_segment_fixed_size 0
		.amdhsa_kernarg_size 448
		.amdhsa_user_sgpr_count 2
		.amdhsa_user_sgpr_dispatch_ptr 0
		.amdhsa_user_sgpr_queue_ptr 0
		.amdhsa_user_sgpr_kernarg_segment_ptr 1
		.amdhsa_user_sgpr_dispatch_id 0
		.amdhsa_user_sgpr_kernarg_preload_length 0
		.amdhsa_user_sgpr_kernarg_preload_offset 0
		.amdhsa_user_sgpr_private_segment_size 0
		.amdhsa_uses_dynamic_stack 0
		.amdhsa_enable_private_segment 0
		.amdhsa_system_sgpr_workgroup_id_x 1
		.amdhsa_system_sgpr_workgroup_id_y 0
		.amdhsa_system_sgpr_workgroup_id_z 0
		.amdhsa_system_sgpr_workgroup_info 0
		.amdhsa_system_vgpr_workitem_id 2
		.amdhsa_next_free_vgpr 256
		.amdhsa_next_free_sgpr 102
		.amdhsa_accum_offset 256
		.amdhsa_reserve_vcc 1
		.amdhsa_float_round_mode_32 0
		.amdhsa_float_round_mode_16_64 0
		.amdhsa_float_denorm_mode_32 3
		.amdhsa_float_denorm_mode_16_64 3
		.amdhsa_dx10_clamp 1
		.amdhsa_ieee_mode 1
		.amdhsa_fp16_overflow 0
		.amdhsa_tg_split 0
		.amdhsa_exception_fp_ieee_invalid_op 0
		.amdhsa_exception_fp_denorm_src 0
		.amdhsa_exception_fp_ieee_div_zero 0
		.amdhsa_exception_fp_ieee_overflow 0
		.amdhsa_exception_fp_ieee_underflow 0
		.amdhsa_exception_fp_ieee_inexact 0
		.amdhsa_exception_int_div_zero 0
	.end_amdhsa_kernel

; __global__ void __launch_bounds__(512, 2) fwd_kernel(Args args) {
;     extern __shared__ __attribute__((aligned(16))) unsigned char lds_raw[];
amdhsa.kernels:
  - .agpr_count:     0
    .args:
      - .offset:         0
        .size:           192
        .value_kind:     by_value
      - .offset:         192
        .size:           4
        .value_kind:     hidden_block_count_x
      - .offset:         196
        .size:           4
        .value_kind:     hidden_block_count_y
      - .offset:         200
        .size:           4
        .value_kind:     hidden_block_count_z
      - .offset:         204
        .size:           2
        .value_kind:     hidden_group_size_x
      - .offset:         206
        .size:           2
        .value_kind:     hidden_group_size_y
      - .offset:         208
        .size:           2
        .value_kind:     hidden_group_size_z
      - .offset:         210
        .size:           2
        .value_kind:     hidden_remainder_x
      - .offset:         212
        .size:           2
        .value_kind:     hidden_remainder_y
      - .offset:         214
        .size:           2
        .value_kind:     hidden_remainder_z
      - .offset:         232
        .size:           8
        .value_kind:     hidden_global_offset_x
      - .offset:         240
        .size:           8
        .value_kind:     hidden_global_offset_y
      - .offset:         248
        .size:           8
        .value_kind:     hidden_global_offset_z
      - .offset:         256
        .size:           2
        .value_kind:     hidden_grid_dims
      - .offset:         280
        .size:           8
        .value_kind:     hidden_multigrid_sync_arg
      - .offset:         312
        .size:           4
        .value_kind:     hidden_dynamic_lds_size
    .group_segment_fixed_size: 0
    .kernarg_segment_align: 8
    .kernarg_segment_size: 448
    .language:       OpenCL C
    .language_version:
      - 2
      - 0
    .max_flat_workgroup_size: 512
    .name:           _Z10fwd_kernel4Args
    .private_segment_fixed_size: 0
    .sgpr_count:     108
    .sgpr_spill_count: 111
    .symbol:         _Z10fwd_kernel4Args.kd
    .uniform_work_group_size: 1
    .uses_dynamic_stack: false
    .vgpr_count:     256
    .vgpr_spill_count: 0
    .wavefront_size: 64
